# split-phase in-proj->X barrier for the idle-round workgroups: arrive after their third tile, run both differential-attention items, wait afterwards
# speedup vs baseline: 1.0155x; 1.0155x over previous
; __device__ void phase_x(const Params& p, int layer, unsigned char* smem) {
;   constexpr int NA = 8 * 4 * 32, NC = 2 * 8 * 2 * 8, NBI = 8 * 2 * 32;
;   const int G = gridDim.x;
;   for (int i = blockIdx.x; i < NA / 2; i += G) {
; #pragma unroll 1
;     for (int h = 0; h < 2; ++h) {
;       int it = h ? (NA - 1 - i) : i;
;       int qt = 31 - (it >> 5); int r = it & 31; int b = r >> 2, hd = r & 3;
;       item_diff(p, layer, b, hd, qt, smem);
;     }
;   }
.LBB0_192:
	s_and_b64 vcc, exec, s[0:1]
	s_cbranch_vccz .LBB0_280
	v_readlane_b32 s0, v253, 3
	v_readlane_b32 s1, v253, 4
	s_load_dword s8, s[0:1], 0x0
	v_readlane_b32 s0, v254, 2
	v_readlane_b32 s1, v254, 3
	s_andn2_b64 vcc, exec, s[0:1]
	s_mov_b64 s[60:61], 0x200
	v_readlane_b32 s18, v255, 60
	s_cmp_lg_u32 s18, 1
	s_cbranch_scc1 .Lxh1_done
	v_readlane_b32 s18, v255, 63
	s_cmp_eq_u32 s18, 0
	s_cbranch_scc1 .LBB0_229
	v_readlane_b32 s18, v255, 61
	s_cmp_lg_u32 s18, 2
	s_cbranch_scc1 .Lxh1_done
	v_writelane_b32 v255, s87, 61
	s_branch .LBB0_229

; __device__ __forceinline__ unsigned xb_ld(unsigned* p)              { return __hip_atomic_load(p, __ATOMIC_RELAXED, __HIP_MEMORY_SCOPE_AGENT); }
; __device__ __forceinline__ unsigned xb_add(unsigned* p, unsigned v) { return __hip_atomic_fetch_add(p, v, __ATOMIC_RELAXED, __HIP_MEMORY_SCOPE_AGENT); }
; #define XB_SPIN(cond, bar) do { unsigned _sp = 0; while (cond) { __builtin_amdgcn_s_sleep(1); \
;     if ((++_sp & 255u) == 0u) { if (xb_ld(&(bar)[XB_TMO])) break; if (_sp > XB_SPIN_CAP) { atomicAdd(&(bar)[XB_TMO], 1u); break; } } } } while (0)
; __device__ __forceinline__ void xcd_barrier(const XcdBarrier& b) {
;     asm volatile("s_waitcnt vmcnt(0)" ::: "memory");
;     __syncthreads();
;     if (threadIdx.x == 0) {
;         unsigned* bar = b.bar;
;         __builtin_amdgcn_s_waitcnt(0);
;         unsigned nloc = b.st[0], nx = b.st[1];
;         if (nloc == 0u) { xcd_barrier_complete(bar, b.x, nloc, nx); b.st[0] = nloc; b.st[1] = nx; }
;         const unsigned old = xb_add(&bar[XB_XSUB(b.x)], 1u);
;         const unsigned gen = old / nloc;
;         if (old + 1u == (gen + 1u) * nloc) {
;             __builtin_amdgcn_fence(__ATOMIC_RELEASE, "agent");
;             asm volatile("s_waitcnt vmcnt(0)" ::: "memory");
;             const unsigned og = xb_add(&bar[XB_TOP], 1u);
;             const unsigned tg = og / nx;
;             if (og + 1u == (tg + 1u) * nx) xb_add(&bar[XB_TOPGEN], 1u);
;             else XB_SPIN(xb_ld(&bar[XB_TOPGEN]) == tg, bar);
;             __builtin_amdgcn_fence(__ATOMIC_ACQUIRE, "agent");
;             xb_add(&bar[XB_XGEN(b.x)], 1u);
;             asm volatile("s_waitcnt vmcnt(0)" ::: "memory");
;         } else {
;             XB_SPIN(xb_ld(&bar[XB_XGEN(b.x)]) == gen, bar);
;             __builtin_amdgcn_fence(__ATOMIC_ACQUIRE, "agent");
;             asm volatile("s_waitcnt vmcnt(0)" ::: "memory");
;         }
;     }
;     __syncthreads();
; }
; __global__ void __launch_bounds__(256, 2) hybrid_megakernel(Params p, int ph_lo, int ph_hi) {
;     ...
;     if (ph + 1 < ph_hi) {
;       if (ph_hi > 1000) cg::this_grid().sync();
;       xcd_barrier(xb);
;     }
.Llb_have:
	s_cmp_lg_u32 s0, 1
	s_cbranch_scc1 .Llb_global
	s_lshr_b32 s1, 0x21084, s52
	s_bitcmp1_b32 s1, 0
	s_cbranch_scc0 .Lea_no
	v_readlane_b32 s1, v253, 0
	s_cmpk_lt_u32 s1, 0x140
	s_cbranch_scc1 .Lea_no
	v_readlane_b32 s1, v255, 61
	s_cmp_eq_u32 s1, 2
	s_cbranch_scc1 .Lea_wait
	s_waitcnt vmcnt(0) lgkmcnt(0)
	s_barrier
	v_cmp_eq_u32_e32 vcc, 0, v210
	s_and_saveexec_b64 s[0:1], vcc
	s_cbranch_execz .Lea_x
	v_readlane_b32 s6, v255, 58
	v_readlane_b32 s7, v255, 59
	v_mov_b32_e32 v0, 1
	s_nop 3
	global_atomic_add v0, v1, v0, s[6:7] sc0
	s_waitcnt vmcnt(0)
	v_readfirstlane_b32 s8, v0
	s_lshr_b32 s9, s8, 6
	v_writelane_b32 v255, s9, 53
	s_and_b32 s8, s8, 63
	s_cmp_lg_u32 s8, 63
	s_cbranch_scc1 .Lea_x
	v_mov_b32_e32 v0, 1
	global_atomic_add v1, v0, s[6:7] offset:1024
.Lea_x:
	s_or_b64 exec, exec, s[0:1]
	s_mov_b32 s1, 1
	v_writelane_b32 v255, s1, 61
	v_writelane_b32 v255, s1, 63
	s_add_i32 s52, s52, 1
	s_branch .LBB0_10
.Lea_wait:
	v_cmp_eq_u32_e32 vcc, 0, v210
	s_and_saveexec_b64 s[0:1], vcc
	s_cbranch_execz .Lew_x
	v_readlane_b32 s6, v255, 58
	v_readlane_b32 s7, v255, 59
	v_readlane_b32 s9, v255, 53
	s_mov_b32 s8, 0
	s_nop 3
.Lew_p:
	global_load_dword v0, v1, s[6:7] offset:1024 sc1
	s_waitcnt vmcnt(0)
	v_readfirstlane_b32 s18, v0
	s_cmp_gt_u32 s18, s9
	s_cbranch_scc1 .Lew_a
	s_sleep 1
	s_add_i32 s8, s8, 1
	s_cmp_lt_u32 s8, 0x100000
	s_cbranch_scc1 .Lew_p
.Lew_a:
	buffer_inv sc1
	s_waitcnt vmcnt(0)
.Lew_x:
	s_or_b64 exec, exec, s[0:1]
	s_barrier
	s_branch .LBB0_9
.Lea_no:
	s_lshr_b32 s1, 0x42108, s52
	s_bitcmp1_b32 s1, 0
	s_cbranch_scc1 .Lxbar
	s_lshr_b32 s1, 0x1ffffc, s52
	s_bitcmp1_b32 s1, 0
	s_cbranch_scc0 .Llb_global
	s_waitcnt vmcnt(0) lgkmcnt(0)
	s_barrier
	v_cmp_eq_u32_e32 vcc, 0, v210
	s_and_saveexec_b64 s[0:1], vcc
	s_cbranch_execz .Llbar_x
	v_readlane_b32 s6, v255, 58
	v_readlane_b32 s7, v255, 59
	v_mov_b32_e32 v0, 1
	s_nop 3
	global_atomic_add v0, v1, v0, s[6:7] sc0
	s_waitcnt vmcnt(0)
	v_readfirstlane_b32 s8, v0
	s_lshr_b32 s9, s8, 6
	s_and_b32 s8, s8, 63
	s_cmp_lg_u32 s8, 63
	s_cbranch_scc1 .Llbar_poll
	v_mov_b32_e32 v0, 1
	global_atomic_add v1, v0, s[6:7] offset:1024
	s_branch .Llbar_acq
